# P0: transpose and rope items at wave priority 2, RMSnorm items at 0
# speedup vs baseline: 1.0041x; 1.0041x over previous
.LBB0_20:
	s_setprio 2
	s_cmpk_gt_i32 s2, 0x7ff
	s_mov_b64 s[12:13], -1
	s_cbranch_scc0 .LBB0_133
	s_cmpk_gt_u32 s2, 0xd67
	s_cbranch_scc0 .LBB0_37
	s_cmpk_lg_i32 s2, 0xf68
	s_cbranch_scc0 .LBB0_32
	v_lshl_add_u32 v36, s2, 8, v66
	v_lshrrev_b32_e32 v0, 5, v36
	v_cvt_f32_u32_e32 v0, v0
	s_brev_b32 s12, 18
	v_mul_f32_e32 v0, v67, v0
	v_and_b32_e32 v1, 0x7fffffff, v0
	v_lshrrev_b32_e32 v2, 23, v1
	v_and_b32_e32 v3, 0x7fffff, v1
	v_cmp_nlt_f32_e64 s[26:27], |v0|, s12
	v_add_u32_e32 v5, 0xffffff88, v2
	v_or_b32_e32 v4, 0x800000, v3
	s_and_saveexec_b64 s[12:13], s[26:27]
	s_xor_b64 s[28:29], exec, s[12:13]
	s_cbranch_execz .LBB0_25
	v_cmp_lt_u32_e32 vcc, 63, v5
	v_mov_b32_e32 v7, v37
	v_mov_b32_e32 v9, v37
	v_cndmask_b32_e32 v2, 0, v90, vcc
	v_add_u32_e32 v2, v2, v5
	v_cmp_lt_u32_e64 s[12:13], 31, v2
	v_mov_b32_e32 v11, v37
	v_mov_b32_e32 v13, v37
	v_cndmask_b32_e64 v3, 0, v91, s[12:13]
	v_add_u32_e32 v2, v3, v2
	v_cmp_lt_u32_e64 s[14:15], 31, v2
	v_mov_b32_e32 v15, v37
	v_mov_b32_e32 v17, v37
	v_cndmask_b32_e64 v3, 0, v91, s[14:15]
	v_add_u32_e32 v18, v3, v2
	v_mad_u64_u32 v[2:3], s[16:17], v4, s48, 0
	v_mov_b32_e32 v6, v3
	v_mad_u64_u32 v[6:7], s[16:17], v4, s49, v[6:7]
	v_mov_b32_e32 v8, v7
	v_mad_u64_u32 v[8:9], s[16:17], v4, s50, v[8:9]
	v_mov_b32_e32 v10, v9
	v_mad_u64_u32 v[10:11], s[16:17], v4, s51, v[10:11]
	v_mov_b32_e32 v12, v11
	v_mad_u64_u32 v[12:13], s[16:17], v4, s52, v[12:13]
	v_mov_b32_e32 v14, v13
	v_mad_u64_u32 v[14:15], s[16:17], v4, s53, v[14:15]
	v_mov_b32_e32 v16, v15
	v_mad_u64_u32 v[16:17], s[16:17], v4, s54, v[16:17]
	v_cndmask_b32_e32 v3, v14, v10, vcc
	v_cndmask_b32_e32 v7, v16, v12, vcc
	v_cndmask_b32_e32 v11, v17, v14, vcc
	v_cndmask_b32_e64 v9, v7, v3, s[12:13]
	v_cndmask_b32_e64 v7, v11, v7, s[12:13]
	v_cndmask_b32_e32 v11, v12, v8, vcc
	v_cndmask_b32_e64 v3, v3, v11, s[12:13]
	v_cndmask_b32_e32 v6, v10, v6, vcc
	v_cndmask_b32_e64 v7, v7, v9, s[14:15]
	v_cndmask_b32_e64 v9, v9, v3, s[14:15]
	v_sub_u32_e32 v12, 32, v18
	v_cndmask_b32_e64 v10, v11, v6, s[12:13]
	v_alignbit_b32 v13, v7, v9, v12
	v_cmp_eq_u32_e64 s[16:17], 0, v18
	v_cndmask_b32_e64 v3, v3, v10, s[14:15]
	v_alignbit_b32 v11, v9, v3, v12
	v_cndmask_b32_e64 v7, v13, v7, s[16:17]
	v_cndmask_b32_e32 v2, v8, v2, vcc
	v_cndmask_b32_e64 v9, v11, v9, s[16:17]
	v_bfe_u32 v14, v7, 29, 1
	v_cndmask_b32_e64 v2, v6, v2, s[12:13]
	v_alignbit_b32 v11, v7, v9, 30
	v_sub_u32_e32 v15, 0, v14
	v_cndmask_b32_e64 v2, v10, v2, s[14:15]
	v_xor_b32_e32 v11, v11, v15
	v_alignbit_b32 v6, v3, v2, v12
	v_cndmask_b32_e64 v3, v6, v3, s[16:17]
	v_ffbh_u32_e32 v8, v11
	v_alignbit_b32 v6, v9, v3, 30
	v_min_u32_e32 v8, 32, v8
	v_alignbit_b32 v2, v3, v2, 30
	v_xor_b32_e32 v6, v6, v15
	v_sub_u32_e32 v9, 31, v8
	v_xor_b32_e32 v2, v2, v15
	v_alignbit_b32 v10, v11, v6, v9
	v_alignbit_b32 v2, v6, v2, v9
	v_alignbit_b32 v3, v10, v2, 9
	v_ffbh_u32_e32 v6, v3
	v_min_u32_e32 v6, 32, v6
	v_lshrrev_b32_e32 v13, 29, v7
	v_not_b32_e32 v9, v6
	v_alignbit_b32 v2, v3, v2, v9
	v_lshlrev_b32_e32 v3, 31, v13
	v_or_b32_e32 v9, 0x33000000, v3
	v_add_lshl_u32 v6, v6, v8, 23
	v_lshrrev_b32_e32 v2, 9, v2
	v_sub_u32_e32 v6, v9, v6
	v_or_b32_e32 v3, 0.5, v3
	v_lshlrev_b32_e32 v8, 23, v8
	v_or_b32_e32 v2, v6, v2
	v_lshrrev_b32_e32 v6, 9, v10
	v_sub_u32_e32 v3, v3, v8
	v_or_b32_e32 v3, v6, v3
	v_mul_f32_e32 v6, 0x3fc90fda, v3
	v_fma_f32 v8, v3, s55, -v6
	v_fmac_f32_e32 v8, 0x33a22168, v3
	v_fmac_f32_e32 v8, 0x3fc90fda, v2
	v_lshrrev_b32_e32 v2, 30, v7
	v_add_f32_e32 v3, v6, v8
	v_add_u32_e32 v2, v14, v2

.LBB0_133:
	s_andn2_b64 vcc, exec, s[12:13]
	s_cbranch_vccnz .LBB0_19
	s_setprio 0
	s_lshl_b32 s12, s2, 3
	s_add_i32 s14, s12, s3
	s_ashr_i32 s15, s14, 31
	s_lshl_b64 s[12:13], s[14:15], 12
	v_lshl_add_u64 v[30:31], v[48:49], 0, s[12:13]
	v_and_b32_e32 v16, 64, v93
	global_load_dwordx4 v[12:15], v[46:47], off
	global_load_dwordx4 v[8:11], v[46:47], off offset:1024
	global_load_dwordx4 v[4:7], v[46:47], off offset:2048
	global_load_dwordx4 v[0:3], v[46:47], off offset:3072
	v_add_u32_e32 v36, 64, v16
	global_load_dwordx4 v[16:19], v[30:31], off
	global_load_dwordx4 v[20:23], v[30:31], off offset:1024
	s_or_b32 s12, s14, 1
	s_ashr_i32 s13, s12, 31
	s_lshl_b64 s[16:17], s[12:13], 12
	v_lshl_add_u64 v[24:25], v[48:49], 0, s[16:17]
	s_lshl_b64 s[14:15], s[14:15], 11
	s_lshl_b64 s[12:13], s[12:13], 11
	s_waitcnt vmcnt(1)
	v_mov_b32_e32 v28, v17
	s_waitcnt vmcnt(0)
	v_mov_b32_e32 v29, v21
	v_mov_b32_e32 v26, v16
	v_mov_b32_e32 v27, v20
	v_pk_mul_f32 v[28:29], v[28:29], v[28:29]
	v_mov_b32_e32 v52, v18
	v_mov_b32_e32 v53, v22
	v_pk_fma_f32 v[26:27], v[26:27], v[26:27], v[28:29]
	v_mov_b32_e32 v54, v19
	v_mov_b32_e32 v55, v23
	v_pk_fma_f32 v[26:27], v[52:53], v[52:53], v[26:27]
	s_nop 0
	v_pk_fma_f32 v[52:53], v[54:55], v[54:55], v[26:27]
	global_load_dwordx4 v[26:29], v[30:31], off offset:2048
	global_load_dwordx4 v[60:63], v[30:31], off offset:3072
	v_add_f32_e32 v52, v52, v53
	s_waitcnt vmcnt(1)
	v_mov_b32_e32 v54, v27
	s_waitcnt vmcnt(0)
	v_mov_b32_e32 v55, v61
	v_mov_b32_e32 v30, v26
	v_mov_b32_e32 v31, v60
	v_pk_mul_f32 v[54:55], v[54:55], v[54:55]
	v_mov_b32_e32 v56, v28
	v_mov_b32_e32 v57, v62
	v_pk_fma_f32 v[30:31], v[30:31], v[30:31], v[54:55]
	v_mov_b32_e32 v58, v29
	v_mov_b32_e32 v59, v63
	v_pk_fma_f32 v[30:31], v[56:57], v[56:57], v[30:31]
	v_lshl_add_u64 v[54:55], v[50:51], 0, s[14:15]
	v_pk_fma_f32 v[30:31], v[58:59], v[58:59], v[30:31]
	s_nop 0
	v_add_f32_e32 v30, v52, v30
	v_add_f32_e32 v30, v30, v31
	v_xor_b32_e32 v31, 32, v93
	v_cmp_lt_i32_e32 vcc, v31, v36
	s_nop 1
	v_cndmask_b32_e32 v31, v93, v31, vcc
	v_lshlrev_b32_e32 v99, 2, v31
	ds_bpermute_b32 v31, v99, v30
	s_waitcnt lgkmcnt(0)
	v_add_f32_e32 v30, v30, v31
	v_xor_b32_e32 v31, 16, v93
	v_cmp_lt_i32_e32 vcc, v31, v36
	s_nop 1
	v_cndmask_b32_e32 v31, v93, v31, vcc
	v_lshlrev_b32_e32 v98, 2, v31
	ds_bpermute_b32 v31, v98, v30
	s_waitcnt lgkmcnt(0)
	v_add_f32_e32 v30, v30, v31
	v_xor_b32_e32 v31, 8, v93
	v_cmp_lt_i32_e32 vcc, v31, v36
	s_nop 1
	v_cndmask_b32_e32 v31, v93, v31, vcc
	v_lshlrev_b32_e32 v97, 2, v31
	ds_bpermute_b32 v31, v97, v30
	s_waitcnt lgkmcnt(0)
	v_add_f32_e32 v30, v30, v31
	v_xor_b32_e32 v31, 4, v93
	v_cmp_lt_i32_e32 vcc, v31, v36
	s_nop 1
	v_cndmask_b32_e32 v31, v93, v31, vcc
	v_lshlrev_b32_e32 v95, 2, v31
	ds_bpermute_b32 v31, v95, v30
	s_waitcnt lgkmcnt(0)
	v_add_f32_e32 v30, v30, v31
	v_xor_b32_e32 v31, 2, v93
	v_cmp_lt_i32_e32 vcc, v31, v36
	s_nop 1
	v_cndmask_b32_e32 v31, v93, v31, vcc
	v_lshlrev_b32_e32 v94, 2, v31
	ds_bpermute_b32 v31, v94, v30
	s_waitcnt lgkmcnt(0)
	v_add_f32_e32 v30, v30, v31
	v_xor_b32_e32 v31, 1, v93
	v_cmp_lt_i32_e32 vcc, v31, v36
	s_nop 1
	v_cndmask_b32_e32 v31, v93, v31, vcc
	v_lshlrev_b32_e32 v36, 2, v31
	ds_bpermute_b32 v31, v36, v30
	s_waitcnt lgkmcnt(0)
	v_add_f32_e32 v30, v30, v31
	v_fmamk_f32 v30, v30, 0x3a800000, v89
	v_cmp_gt_f32_e32 vcc, s47, v30
	v_mul_f32_e32 v31, 0x4b800000, v30
	s_nop 0
	v_cndmask_b32_e32 v30, v30, v31, vcc
	v_rsq_f32_e32 v30, v30
	s_nop 0
	v_mul_f32_e32 v31, 0x45800000, v30
	v_cndmask_b32_e32 v30, v30, v31, vcc
	v_mul_f32_e32 v16, v16, v30
	v_mul_f32_e32 v17, v17, v30
	v_mul_f32_e32 v16, v12, v16
	v_mul_f32_e32 v17, v13, v17
	v_cvt_pk_bf16_f32 v52, v16, v17
	v_mul_f32_e32 v16, v18, v30
	v_mul_f32_e32 v17, v19, v30
	v_mul_f32_e32 v16, v14, v16
	v_mul_f32_e32 v17, v15, v17
	v_cvt_pk_bf16_f32 v53, v16, v17
	v_mul_f32_e32 v16, v20, v30
	v_mul_f32_e32 v17, v21, v30
	v_mul_f32_e32 v16, v8, v16
	v_mul_f32_e32 v17, v9, v17
	v_cvt_pk_bf16_f32 v56, v16, v17
	v_mul_f32_e32 v16, v22, v30
	v_mul_f32_e32 v17, v23, v30
	v_mul_f32_e32 v16, v10, v16
	v_mul_f32_e32 v17, v11, v17
	v_cvt_pk_bf16_f32 v57, v16, v17
	v_mul_f32_e32 v16, v26, v30
	v_mul_f32_e32 v17, v27, v30
	v_mul_f32_e32 v16, v4, v16
	v_mul_f32_e32 v17, v5, v17
	v_cvt_pk_bf16_f32 v58, v16, v17
	v_mul_f32_e32 v16, v28, v30
	v_mul_f32_e32 v17, v29, v30
	v_mul_f32_e32 v16, v6, v16
	v_mul_f32_e32 v17, v7, v17
	v_cvt_pk_bf16_f32 v59, v16, v17
	v_mul_f32_e32 v16, v60, v30
	v_mul_f32_e32 v17, v61, v30
	v_mul_f32_e32 v16, v0, v16
	v_mul_f32_e32 v17, v1, v17
	v_cvt_pk_bf16_f32 v60, v16, v17
	v_mul_f32_e32 v16, v62, v30
	v_mul_f32_e32 v17, v63, v30
	v_mul_f32_e32 v16, v2, v16
	v_mul_f32_e32 v17, v3, v17
	v_cvt_pk_bf16_f32 v61, v16, v17
	global_load_dwordx4 v[20:23], v[24:25], off
	global_load_dwordx4 v[16:19], v[24:25], off offset:1024
	s_waitcnt vmcnt(1)
	v_mov_b32_e32 v28, v21
	s_waitcnt vmcnt(0)
	v_mov_b32_e32 v29, v17
	v_mov_b32_e32 v26, v20
	v_mov_b32_e32 v27, v16
	v_pk_mul_f32 v[28:29], v[28:29], v[28:29]
	v_mov_b32_e32 v30, v22
	v_mov_b32_e32 v31, v18
	v_pk_fma_f32 v[26:27], v[26:27], v[26:27], v[28:29]
	v_mov_b32_e32 v62, v23
	v_mov_b32_e32 v63, v19
	v_pk_fma_f32 v[26:27], v[30:31], v[30:31], v[26:27]
	s_nop 0
	v_pk_fma_f32 v[62:63], v[62:63], v[62:63], v[26:27]
	global_load_dwordx4 v[28:31], v[24:25], off offset:2048
	s_nop 0
	global_load_dwordx4 v[24:27], v[24:25], off offset:3072
	s_nop 0
	global_store_dwordx2 v[54:55], v[52:53], off
	global_store_dwordx2 v[54:55], v[56:57], off offset:512
	global_store_dwordx2 v[54:55], v[58:59], off offset:1024
	global_store_dwordx2 v[54:55], v[60:61], off offset:1536
	v_add_f32_e32 v54, v62, v63
	s_waitcnt vmcnt(5)
	v_mov_b32_e32 v102, v29
	s_waitcnt vmcnt(4)
	v_mov_b32_e32 v103, v25
	v_mov_b32_e32 v100, v28
	v_mov_b32_e32 v101, v24
	v_pk_mul_f32 v[52:53], v[102:103], v[102:103]
	v_mov_b32_e32 v108, v30
	v_mov_b32_e32 v109, v26
	v_pk_fma_f32 v[52:53], v[100:101], v[100:101], v[52:53]
	v_mov_b32_e32 v110, v31
	v_mov_b32_e32 v111, v27
	v_pk_fma_f32 v[52:53], v[108:109], v[108:109], v[52:53]
	s_nop 0
	v_pk_fma_f32 v[52:53], v[110:111], v[110:111], v[52:53]
	s_nop 0
	v_add_f32_e32 v52, v54, v52
	v_add_f32_e32 v52, v52, v53
	ds_bpermute_b32 v53, v99, v52
	s_waitcnt lgkmcnt(0)
	v_add_f32_e32 v52, v52, v53
	ds_bpermute_b32 v53, v98, v52
	s_waitcnt lgkmcnt(0)
	v_add_f32_e32 v52, v52, v53
	ds_bpermute_b32 v53, v97, v52
	s_waitcnt lgkmcnt(0)
	v_add_f32_e32 v52, v52, v53
	ds_bpermute_b32 v53, v95, v52
	s_waitcnt lgkmcnt(0)
	v_add_f32_e32 v52, v52, v53
	ds_bpermute_b32 v53, v94, v52
	s_waitcnt lgkmcnt(0)
	v_add_f32_e32 v52, v52, v53
	ds_bpermute_b32 v36, v36, v52
	s_waitcnt lgkmcnt(0)
	v_add_f32_e32 v36, v52, v36
	v_fmamk_f32 v36, v36, 0x3a800000, v89
	v_cmp_gt_f32_e32 vcc, s47, v36
	v_mul_f32_e32 v52, 0x4b800000, v36
	s_nop 0
	v_cndmask_b32_e32 v36, v36, v52, vcc
	v_rsq_f32_e32 v36, v36
	s_nop 0
	v_mul_f32_e32 v52, 0x45800000, v36
	v_cndmask_b32_e32 v36, v36, v52, vcc
	v_mul_f32_e32 v20, v20, v36
	v_mul_f32_e32 v12, v12, v20
	v_mul_f32_e32 v20, v21, v36
	v_mul_f32_e32 v13, v13, v20
	v_cvt_pk_bf16_f32 v12, v12, v13
	v_mul_f32_e32 v13, v22, v36
	v_mul_f32_e32 v13, v14, v13
	v_mul_f32_e32 v14, v23, v36
	v_mul_f32_e32 v14, v15, v14
	v_cvt_pk_bf16_f32 v13, v13, v14
	v_lshl_add_u64 v[14:15], v[50:51], 0, s[12:13]
	global_store_dwordx2 v[14:15], v[12:13], off
	v_mul_f32_e32 v12, v16, v36
	v_mul_f32_e32 v8, v8, v12
	v_mul_f32_e32 v12, v17, v36
	v_mul_f32_e32 v9, v9, v12
	v_cvt_pk_bf16_f32 v8, v8, v9
	v_mul_f32_e32 v9, v18, v36
	v_mul_f32_e32 v9, v10, v9
	v_mul_f32_e32 v10, v19, v36
	v_mul_f32_e32 v10, v11, v10
	v_cvt_pk_bf16_f32 v9, v9, v10
	global_store_dwordx2 v[14:15], v[8:9], off offset:512
	v_mul_f32_e32 v8, v28, v36
	v_mul_f32_e32 v4, v4, v8
	v_mul_f32_e32 v8, v29, v36
	v_mul_f32_e32 v5, v5, v8
	v_cvt_pk_bf16_f32 v4, v4, v5
	v_mul_f32_e32 v5, v30, v36
	v_mul_f32_e32 v5, v6, v5
	v_mul_f32_e32 v6, v31, v36
	v_mul_f32_e32 v6, v7, v6
	v_cvt_pk_bf16_f32 v5, v5, v6
	global_store_dwordx2 v[14:15], v[4:5], off offset:1024
	v_mul_f32_e32 v4, v24, v36
	v_mul_f32_e32 v0, v0, v4
	v_mul_f32_e32 v4, v25, v36
	v_mul_f32_e32 v1, v1, v4
	v_cvt_pk_bf16_f32 v0, v0, v1
	v_mul_f32_e32 v1, v26, v36
	v_mul_f32_e32 v1, v2, v1
	v_mul_f32_e32 v2, v27, v36
	v_mul_f32_e32 v2, v3, v2
	v_cvt_pk_bf16_f32 v1, v1, v2
	global_store_dwordx2 v[14:15], v[0:1], off offset:1536
	s_branch .LBB0_19

.LBB0_136:
	s_setprio 0
	v_readlane_b32 s60, v250, 56
	v_readlane_b32 s61, v250, 57
	v_readlane_b32 s40, v250, 40
	v_readlane_b32 s41, v250, 41
	v_readlane_b32 s42, v250, 42
	v_readlane_b32 s43, v250, 43
	v_readlane_b32 s44, v250, 44
	v_readlane_b32 s45, v250, 45
	v_readlane_b32 s46, v250, 46
	v_readlane_b32 s47, v250, 47
	v_readlane_b32 s48, v250, 48
	v_readlane_b32 s49, v250, 49
	v_readlane_b32 s50, v250, 50
	v_readlane_b32 s51, v250, 51
	v_readlane_b32 s52, v250, 52
	v_readlane_b32 s53, v250, 53
	v_readlane_b32 s54, v250, 54
	v_readlane_b32 s55, v250, 55
.LBB0_137:
	s_setprio 0
	s_waitcnt vmcnt(0)
	s_barrier
	s_and_saveexec_b64 s[0:1], s[10:11]
	s_xor_b64 s[0:1], exec, s[0:1]
	s_lshl_b32 s2, s33, 6
	s_mov_b32 s3, 0
	s_or_saveexec_b64 s[0:1], s[0:1]
	v_mov_b64_e32 v[98:99], s[2:3]
	s_xor_b64 exec, exec, s[0:1]
	s_cbranch_execz .LBB0_192
	v_mov_b32_e32 v0, 0x12000
	s_waitcnt vmcnt(0) expcnt(0) lgkmcnt(0)
	ds_read_b32 v2, v0
	v_mov_b32_e32 v0, 0x12004
	ds_read_b32 v0, v0
	s_waitcnt lgkmcnt(1)
	v_cmp_ne_u32_e32 vcc, 0, v2
	s_cbranch_vccnz .LBB0_155
	s_add_u32 s2, s20, 0x1000
	s_addc_u32 s3, s21, 0
	s_add_u32 s4, s20, 0x1100
	s_addc_u32 s5, s21, 0
	s_add_u32 s6, s20, 0x1200
	s_addc_u32 s7, s21, 0
	s_mul_i32 s16, s23, s36
	s_add_u32 s8, s20, 0x1300
	s_mul_i32 s16, s16, s22
	s_addc_u32 s9, s21, 0
	s_mov_b32 s17, 1
	v_mov_b32_e32 v16, 0
	s_branch .LBB0_143
